# norm1: residual-stream loads software-pipelined one iteration ahead
# speedup vs baseline: 1.0329x; 1.0058x over previous
.LBB0_398:
	v_lshl_add_u64 v[50:51], s[2:3], 0, v[178:179]
	s_add_i32 s11, s6, s7
	s_add_i32 s22, s11, 3
	s_ashr_i32 s23, s22, 31
	s_lshl_b64 s[24:25], s[22:23], 11
	s_lshl_b64 s[38:39], s[22:23], 12
	s_and_b64 vcc, exec, s[8:9]
	s_cbranch_vccz .Ln1_f32
	s_cmp_lg_u32 s7, -2
	s_cbranch_scc1 .Ln1_pf_ready
	v_add_co_u32_e32 v244, vcc, 0x5c00000, v50
	v_lshl_add_u64 v[246:247], v[168:169], 0, s[24:25]
	s_nop 0
	v_addc_co_u32_e32 v245, vcc, 0, v51, vcc
	global_load_dwordx2 v[226:227], v[244:245], off
	global_load_dwordx2 v[228:229], v[244:245], off offset:512
	global_load_dwordx2 v[230:231], v[244:245], off offset:1024
	global_load_dwordx2 v[232:233], v[244:245], off offset:1536
	global_load_dwordx2 v[234:235], v[246:247], off
	global_load_dwordx2 v[236:237], v[246:247], off offset:512
	global_load_dwordx2 v[240:241], v[246:247], off offset:1024
	global_load_dwordx2 v[242:243], v[246:247], off offset:1536
	s_waitcnt vmcnt(0)
	s_branch .Ln1_unpack
.Ln1_pf_ready:
	s_waitcnt vmcnt(8)
.Ln1_unpack:
	v_lshlrev_b32_e32 v18, 16, v226
	v_and_b32_e32 v19, 0xffff0000, v226
	v_lshlrev_b32_e32 v20, 16, v227
	v_and_b32_e32 v21, 0xffff0000, v227
	v_lshlrev_b32_e32 v22, 16, v228
	v_and_b32_e32 v23, 0xffff0000, v228
	v_lshlrev_b32_e32 v24, 16, v229
	v_and_b32_e32 v25, 0xffff0000, v229
	v_lshlrev_b32_e32 v26, 16, v230
	v_and_b32_e32 v27, 0xffff0000, v230
	v_lshlrev_b32_e32 v28, 16, v231
	v_and_b32_e32 v29, 0xffff0000, v231
	v_lshlrev_b32_e32 v30, 16, v232
	v_and_b32_e32 v31, 0xffff0000, v232
	v_lshlrev_b32_e32 v32, 16, v233
	v_and_b32_e32 v33, 0xffff0000, v233
	v_lshlrev_b32_e32 v34, 16, v234
	v_and_b32_e32 v35, 0xffff0000, v234
	v_lshlrev_b32_e32 v36, 16, v235
	v_and_b32_e32 v37, 0xffff0000, v235
	v_lshlrev_b32_e32 v38, 16, v236
	v_and_b32_e32 v39, 0xffff0000, v236
	v_lshlrev_b32_e32 v40, 16, v237
	v_and_b32_e32 v41, 0xffff0000, v237
	v_lshlrev_b32_e32 v42, 16, v240
	v_and_b32_e32 v43, 0xffff0000, v240
	v_lshlrev_b32_e32 v44, 16, v241
	v_and_b32_e32 v45, 0xffff0000, v241
	v_lshlrev_b32_e32 v46, 16, v242
	v_and_b32_e32 v47, 0xffff0000, v242
	v_lshlrev_b32_e32 v48, 16, v243
	v_and_b32_e32 v49, 0xffff0000, v243
	s_cmp_eq_u32 s7, 12
	s_cbranch_scc1 .Ln1_loaded
	s_mov_b64 s[0:1], 0x1000
	v_lshl_add_u64 v[244:245], v[244:245], 0, s[0:1]
	v_lshl_add_u64 v[246:247], v[246:247], 0, s[0:1]
	global_load_dwordx2 v[226:227], v[244:245], off
	global_load_dwordx2 v[228:229], v[244:245], off offset:512
	global_load_dwordx2 v[230:231], v[244:245], off offset:1024
	global_load_dwordx2 v[232:233], v[244:245], off offset:1536
	global_load_dwordx2 v[234:235], v[246:247], off
	global_load_dwordx2 v[236:237], v[246:247], off offset:512
	global_load_dwordx2 v[240:241], v[246:247], off offset:1024
	global_load_dwordx2 v[242:243], v[246:247], off offset:1536
	s_branch .Ln1_loaded
